# zback loop and FFT conv load/store segments: conditional edge loads no longer drain vmcnt one by one (issued together, single wait, deferred shifts)
# speedup vs baseline: 1.0228x; 1.0228x over previous
.LBB0_308:
	s_or_b64 exec, exec, s[40:41]
	s_waitcnt vmcnt(0)
	v_lshlrev_b32_e32 v18, 16, v244
	v_lshlrev_b32_e32 v17, 16, v245
	v_lshlrev_b32_e32 v26, 16, v246
	v_lshlrev_b32_e32 v25, 16, v247
	v_lshlrev_b32_e32 v30, 16, v248
	v_lshlrev_b32_e32 v29, 16, v249
	v_lshlrev_b32_e32 v20, 16, v250
	v_lshlrev_b32_e32 v23, 16, v251
	s_waitcnt vmcnt(1)
	v_lshlrev_b32_e32 v31, 16, v12
	v_and_b32_e32 v12, 0xffff0000, v12
	v_pk_fma_f32 v[38:39], v[84:85], v[30:31], v[90:91]
	v_mov_b32_e32 v30, v31
	v_mov_b32_e32 v31, v12
	v_and_b32_e32 v37, 16, v14
	v_and_b32_e32 v36, 0xffff0000, v13
	v_lshlrev_b32_e32 v13, 16, v13
	v_pk_fma_f32 v[30:31], v[86:87], v[30:31], v[38:39]
	v_lshlrev_b32_e32 v34, 16, v15
	v_pk_fma_f32 v[30:31], v[88:89], v[12:13], v[30:31]
	v_pk_fma_f32 v[38:39], v[84:85], v[12:13], v[90:91]
	v_pk_mov_b32 v[12:13], v[12:13], v[36:37] op_sel:[1,0]
	v_and_b32_e32 v32, 0xffff0000, v14
	v_and_b32_e32 v35, 0xffff0000, v15
	v_mov_b32_e32 v33, v34
	v_lshlrev_b32_e32 v15, 16, v14
	v_mov_b32_e32 v14, v36
	v_pk_fma_f32 v[12:13], v[86:87], v[12:13], v[38:39]
	v_lshlrev_b32_e32 v27, 16, v8
	v_pk_fma_f32 v[36:37], v[88:89], v[14:15], v[12:13]
	v_pk_fma_f32 v[12:13], v[84:85], v[14:15], v[90:91]
	v_pk_mov_b32 v[14:15], v[14:15], v[32:33] op_sel:[1,0]
	v_and_b32_e32 v8, 0xffff0000, v8
	v_pk_fma_f32 v[12:13], v[86:87], v[14:15], v[12:13]
	v_mov_b32_e32 v28, v35
	v_pk_fma_f32 v[38:39], v[88:89], v[32:33], v[12:13]
	v_pk_fma_f32 v[12:13], v[84:85], v[32:33], v[90:91]
	v_and_b32_e32 v33, 16, v10
	v_pk_fma_f32 v[12:13], v[86:87], v[34:35], v[12:13]
	v_pk_fma_f32 v[34:35], v[94:95], v[26:27], v[98:99]
	v_mov_b32_e32 v26, v27
	v_mov_b32_e32 v27, v8
	v_and_b32_e32 v32, 0xffff0000, v9
	v_lshlrev_b32_e32 v9, 16, v9
	v_pk_fma_f32 v[26:27], v[92:93], v[26:27], v[34:35]
	v_lshlrev_b32_e32 v14, 16, v11
	v_pk_fma_f32 v[26:27], v[96:97], v[8:9], v[26:27]
	v_pk_fma_f32 v[34:35], v[94:95], v[8:9], v[98:99]
	v_pk_mov_b32 v[8:9], v[8:9], v[32:33] op_sel:[1,0]
	v_pk_fma_f32 v[28:29], v[88:89], v[28:29], v[12:13]
	v_and_b32_e32 v12, 0xffff0000, v10
	v_and_b32_e32 v15, 0xffff0000, v11
	v_mov_b32_e32 v13, v14
	v_lshlrev_b32_e32 v11, 16, v10
	v_mov_b32_e32 v10, v32
	v_pk_fma_f32 v[8:9], v[92:93], v[8:9], v[34:35]
	v_lshlrev_b32_e32 v19, 16, v0
	v_pk_fma_f32 v[32:33], v[96:97], v[10:11], v[8:9]
	v_pk_fma_f32 v[8:9], v[94:95], v[10:11], v[98:99]
	v_pk_mov_b32 v[10:11], v[10:11], v[12:13] op_sel:[1,0]
	v_and_b32_e32 v0, 0xffff0000, v0
	v_pk_fma_f32 v[8:9], v[92:93], v[10:11], v[8:9]
	v_mov_b32_e32 v24, v15
	v_pk_fma_f32 v[34:35], v[96:97], v[12:13], v[8:9]
	v_pk_fma_f32 v[8:9], v[94:95], v[12:13], v[98:99]
	v_and_b32_e32 v13, 16, v2
	v_pk_fma_f32 v[8:9], v[92:93], v[14:15], v[8:9]
	v_pk_fma_f32 v[14:15], v[84:85], v[18:19], v[90:91]
	v_mov_b32_e32 v18, v19
	v_mov_b32_e32 v19, v0
	v_and_b32_e32 v12, 0xffff0000, v1
	v_lshlrev_b32_e32 v1, 16, v1
	v_pk_fma_f32 v[14:15], v[86:87], v[18:19], v[14:15]
	v_lshlrev_b32_e32 v10, 16, v3
	v_pk_fma_f32 v[14:15], v[88:89], v[0:1], v[14:15]
	v_pk_fma_f32 v[18:19], v[84:85], v[0:1], v[90:91]
	v_pk_mov_b32 v[0:1], v[0:1], v[12:13] op_sel:[1,0]
	v_pk_fma_f32 v[24:25], v[96:97], v[24:25], v[8:9]
	v_and_b32_e32 v8, 0xffff0000, v2
	v_and_b32_e32 v11, 0xffff0000, v3
	v_mov_b32_e32 v9, v10
	v_lshlrev_b32_e32 v3, 16, v2
	v_mov_b32_e32 v2, v12
	v_pk_fma_f32 v[0:1], v[86:87], v[0:1], v[18:19]
	v_mov_b32_e32 v16, v11
	v_pk_fma_f32 v[12:13], v[88:89], v[2:3], v[0:1]
	v_pk_fma_f32 v[0:1], v[84:85], v[2:3], v[90:91]
	v_pk_mov_b32 v[2:3], v[2:3], v[8:9] op_sel:[1,0]
	v_pk_mul_f32 v[14:15], v[14:15], v[26:27]
	v_pk_fma_f32 v[0:1], v[86:87], v[2:3], v[0:1]
	s_waitcnt vmcnt(0)
	v_and_b32_e32 v42, 0xffff0000, v6
	v_pk_fma_f32 v[18:19], v[88:89], v[8:9], v[0:1]
	v_pk_fma_f32 v[0:1], v[84:85], v[8:9], v[90:91]
	v_pk_mul_f32 v[34:35], v[18:19], v[34:35]
	v_pk_fma_f32 v[0:1], v[86:87], v[10:11], v[0:1]
	ds_read2_b64 v[8:11], v215 offset0:2 offset1:3
	v_pk_fma_f32 v[40:41], v[88:89], v[16:17], v[0:1]
	ds_read2_b64 v[0:3], v215 offset1:1
	v_pk_mul_f32 v[24:25], v[40:41], v[24:25]
	v_lshlrev_b32_e32 v21, 16, v4
	v_and_b32_e32 v4, 0xffff0000, v4
	v_pk_fma_f32 v[48:49], v[94:95], v[20:21], v[98:99]
	s_waitcnt lgkmcnt(0)
	v_mov_b32_e32 v16, v0
	v_mov_b32_e32 v17, v2
	v_pk_fma_f32 v[26:27], v[82:83], v[14:15], v[16:17]
	v_pk_mul_f32 v[16:17], v[12:13], v[32:33]
	v_mov_b32_e32 v32, v8
	v_mov_b32_e32 v33, v10
	ds_read2_b64 v[12:15], v215 offset0:4 offset1:5
	v_pk_fma_f32 v[32:33], v[82:83], v[16:17], v[32:33]
	ds_read2_b64 v[16:19], v215 offset0:6 offset1:7
	v_mov_b32_e32 v2, v1
	v_mov_b32_e32 v20, v21
	s_waitcnt lgkmcnt(1)
	v_mov_b32_e32 v44, v12
	v_mov_b32_e32 v45, v14
	s_waitcnt lgkmcnt(0)
	v_mov_b32_e32 v40, v16
	v_mov_b32_e32 v41, v18
	v_pk_fma_f32 v[24:25], v[82:83], v[24:25], v[40:41]
	v_lshlrev_b32_e32 v40, 16, v7
	v_mov_b32_e32 v43, v40
	v_pk_fma_f32 v[34:35], v[82:83], v[34:35], v[44:45]
	v_and_b32_e32 v41, 0xffff0000, v7
	v_pk_fma_f32 v[44:45], v[94:95], v[42:43], v[98:99]
	v_mov_b32_e32 v22, v41
	v_pk_fma_f32 v[44:45], v[92:93], v[40:41], v[44:45]
	v_and_b32_e32 v41, 16, v6
	v_and_b32_e32 v40, 0xffff0000, v5
	v_lshlrev_b32_e32 v5, 16, v5
	v_pk_fma_f32 v[46:47], v[94:95], v[4:5], v[98:99]
	v_pk_mov_b32 v[0:1], v[4:5], v[40:41] op_sel:[1,0]
	v_lshlrev_b32_e32 v7, 16, v6
	v_mov_b32_e32 v6, v40
	v_pk_fma_f32 v[0:1], v[92:93], v[0:1], v[46:47]
	v_mov_b32_e32 v21, v4
	v_pk_fma_f32 v[0:1], v[96:97], v[6:7], v[0:1]
	v_pk_fma_f32 v[20:21], v[92:93], v[20:21], v[48:49]
	v_pk_mul_f32 v[0:1], v[36:37], v[0:1]
	v_mov_b32_e32 v10, v9
	v_pk_fma_f32 v[22:23], v[96:97], v[22:23], v[44:45]
	v_pk_fma_f32 v[44:45], v[94:95], v[6:7], v[98:99]
	v_pk_fma_f32 v[20:21], v[96:97], v[4:5], v[20:21]
	v_pk_fma_f32 v[4:5], v[82:83], v[0:1], v[10:11]
	v_pk_mov_b32 v[0:1], v[6:7], v[42:43] op_sel:[1,0]
	v_mov_b32_e32 v14, v13
	v_pk_fma_f32 v[0:1], v[92:93], v[0:1], v[44:45]
	v_pk_mul_f32 v[20:21], v[30:31], v[20:21]
	v_pk_fma_f32 v[0:1], v[96:97], v[42:43], v[0:1]
	v_mov_b32_e32 v18, v17
	v_pk_mul_f32 v[0:1], v[38:39], v[0:1]
	v_lshlrev_b64 v[10:11], 1, v[70:71]
	v_pk_fma_f32 v[6:7], v[82:83], v[0:1], v[14:15]
	v_pk_mul_f32 v[0:1], v[28:29], v[22:23]
	v_pk_fma_f32 v[20:21], v[82:83], v[20:21], v[2:3]
	v_pk_fma_f32 v[8:9], v[82:83], v[0:1], v[18:19]
	v_cvt_pk_bf16_f32 v0, v26, v27
	v_cvt_pk_bf16_f32 v1, v32, v33
	v_cvt_pk_bf16_f32 v2, v34, v35
	v_cvt_pk_bf16_f32 v3, v24, v25
	v_lshl_add_u64 v[12:13], s[92:93], 0, v[10:11]
	s_add_i32 s80, s80, 1
	global_store_dwordx4 v[12:13], v[0:3], off
	s_cmp_eq_u32 s80, 4
	s_nop 0
	v_cvt_pk_bf16_f32 v0, v20, v21
	v_cvt_pk_bf16_f32 v1, v4, v5
	v_cvt_pk_bf16_f32 v2, v6, v7
	v_cvt_pk_bf16_f32 v3, v8, v9
	v_lshl_add_u64 v[4:5], s[90:91], 0, v[10:11]
	global_store_dwordx4 v[4:5], v[0:3], off
	s_cbranch_scc1 .LBB0_398
.LBB0_309:
	s_lshl_b32 s33, s80, 15
	s_add_u32 s90, s52, s33
	s_addc_u32 s91, s73, 0
	v_lshl_add_u64 v[104:105], v[62:63], 1, s[90:91]
	s_barrier
	global_load_dwordx4 v[0:3], v[104:105], off
	v_mov_b32_e32 v16, 0
	v_lshl_add_u64 v[110:111], v[68:69], 1, s[90:91]
	v_mov_b32_e32 v17, 0
	v_mov_b32_e32 v244, 0
	s_and_saveexec_b64 s[40:41], s[12:13]
	s_cbranch_execz .LBB0_311
	global_load_ushort v244, v[110:111], off offset:-2
	s_nop 0
	s_nop 0
.LBB0_311:
	s_or_b64 exec, exec, s[40:41]
	v_mov_b32_e32 v245, 0
	s_and_saveexec_b64 s[40:41], s[14:15]
	s_cbranch_execz .LBB0_313
	global_load_ushort v245, v[104:105], off offset:16
	s_nop 0
	s_nop 0
.LBB0_313:
	s_or_b64 exec, exec, s[40:41]
	s_lshl_b32 s33, s80, 14
	s_lshl_b32 s33, s33, 1
	s_add_u32 s92, s74, s33
	s_addc_u32 s93, s75, 0
	v_lshl_add_u64 v[106:107], v[62:63], 1, s[92:93]
	global_load_dwordx4 v[8:11], v[106:107], off
	v_mov_b32_e32 v19, 0
	v_lshl_add_u64 v[114:115], v[68:69], 1, s[92:93]
	v_mov_b32_e32 v21, 0
	v_mov_b32_e32 v246, 0
	s_and_saveexec_b64 s[40:41], s[12:13]
	s_cbranch_execz .LBB0_315
	global_load_ushort v246, v[114:115], off offset:-2
	s_nop 0
	s_nop 0
.LBB0_315:
	s_or_b64 exec, exec, s[40:41]
	v_mov_b32_e32 v247, 0
	s_and_saveexec_b64 s[40:41], s[14:15]
	s_cbranch_execz .LBB0_317
	global_load_ushort v247, v[106:107], off offset:16
	s_nop 0
	s_nop 0
.LBB0_317:
	s_or_b64 exec, exec, s[40:41]
	s_add_u32 s94, s90, 0x4000
	s_addc_u32 s95, s91, 0
	v_lshl_add_u64 v[108:109], v[62:63], 1, s[94:95]
	global_load_dwordx4 v[12:15], v[108:109], off
	v_mov_b32_e32 v22, 0
	v_lshl_add_u64 v[116:117], v[68:69], 1, s[94:95]
	v_mov_b32_e32 v23, 0
	v_mov_b32_e32 v248, 0
	s_and_saveexec_b64 s[40:41], s[12:13]
	s_cbranch_execz .LBB0_319
	global_load_ushort v248, v[116:117], off offset:-2
	s_nop 0
	s_nop 0
.LBB0_319:
	s_or_b64 exec, exec, s[40:41]
	v_mov_b32_e32 v249, 0
	s_and_saveexec_b64 s[40:41], s[14:15]
	s_cbranch_execz .LBB0_321
	global_load_ushort v249, v[108:109], off offset:16
	s_nop 0
	s_nop 0
.LBB0_321:
	s_or_b64 exec, exec, s[40:41]
	s_add_u32 s96, s92, 0x4000
	s_addc_u32 s97, s93, 0
	v_lshl_add_u64 v[112:113], v[62:63], 1, s[96:97]
	global_load_dwordx4 v[4:7], v[112:113], off
	v_mov_b32_e32 v18, 0
	v_lshl_add_u64 v[118:119], v[68:69], 1, s[96:97]
	v_mov_b32_e32 v20, 0
	v_mov_b32_e32 v250, 0
	s_and_saveexec_b64 s[40:41], s[12:13]
	s_cbranch_execz .LBB0_323
	global_load_ushort v250, v[118:119], off offset:-2
	s_nop 0
	s_nop 0
.LBB0_323:
	s_or_b64 exec, exec, s[40:41]
	v_mov_b32_e32 v251, 0
	s_and_saveexec_b64 s[40:41], s[14:15]
	s_cbranch_execz .LBB0_325
	global_load_ushort v251, v[112:113], off offset:16
	s_nop 0
	s_nop 0
.LBB0_325:
	s_or_b64 exec, exec, s[40:41]
	s_waitcnt vmcnt(0)
	v_lshlrev_b32_e32 v17, 16, v244
	v_lshlrev_b32_e32 v16, 16, v245
	v_lshlrev_b32_e32 v21, 16, v246
	v_lshlrev_b32_e32 v19, 16, v247
	v_lshlrev_b32_e32 v23, 16, v248
	v_lshlrev_b32_e32 v22, 16, v249
	v_lshlrev_b32_e32 v20, 16, v250
	v_lshlrev_b32_e32 v18, 16, v251
	s_waitcnt vmcnt(1)
	v_and_b32_e32 v29, 0xffff0000, v12
	v_lshlrev_b32_e32 v12, 16, v12
	v_and_b32_e32 v24, 0xffff0000, v15
	v_lshlrev_b32_e32 v26, 16, v15
	v_and_b32_e32 v27, 0xffff0000, v13
	v_lshlrev_b32_e32 v25, 16, v13
	v_fma_f32 v13, v84, v23, v90
	v_fma_f32 v15, v84, v12, v90
	v_and_b32_e32 v28, 0xffff0000, v14
	v_lshlrev_b32_e32 v14, 16, v14
	v_fmac_f32_e32 v13, v86, v12
	v_fmac_f32_e32 v15, v86, v29
	v_fma_f32 v23, v84, v29, v90
	v_fma_f32 v33, v84, v26, v90
	v_fmac_f32_e32 v13, v88, v29
	v_fmac_f32_e32 v15, v88, v25
	v_fmac_f32_e32 v23, v86, v25
	v_fma_f32 v25, v84, v25, v90
	v_fma_f32 v29, v84, v14, v90
	v_fmac_f32_e32 v33, v86, v24
	v_fmac_f32_e32 v23, v88, v27
	v_fmac_f32_e32 v25, v86, v27
	v_fma_f32 v27, v84, v27, v90
	v_fmac_f32_e32 v29, v86, v28
	v_fma_f32 v31, v84, v28, v90
	v_fmac_f32_e32 v33, v88, v22
	v_and_b32_e32 v12, 0xffff0000, v11
	v_lshlrev_b32_e32 v11, 16, v11
	v_lshlrev_b32_e32 v22, 16, v10
	v_fmac_f32_e32 v25, v88, v14
	v_fmac_f32_e32 v27, v86, v14
	v_fmac_f32_e32 v29, v88, v26
	v_fmac_f32_e32 v31, v86, v26
	v_and_b32_e32 v14, 0xffff0000, v10
	v_and_b32_e32 v26, 0xffff0000, v8
	v_lshlrev_b32_e32 v10, 16, v8
	v_fma_f32 v8, v94, v21, v98
	v_fma_f32 v40, v94, v22, v98
	v_fma_f32 v44, v94, v11, v98
	v_fmac_f32_e32 v31, v88, v24
	v_and_b32_e32 v24, 0xffff0000, v9
	v_lshlrev_b32_e32 v9, 16, v9
	v_fmac_f32_e32 v8, v92, v10
	v_fma_f32 v10, v94, v10, v98
	v_fma_f32 v34, v94, v26, v98
	v_fmac_f32_e32 v40, v92, v14
	v_fma_f32 v42, v94, v14, v98
	v_fmac_f32_e32 v44, v92, v12
	v_fmac_f32_e32 v10, v92, v26
	v_fmac_f32_e32 v34, v92, v9
	v_fma_f32 v36, v94, v9, v98
	v_fma_f32 v38, v94, v24, v98
	v_fmac_f32_e32 v40, v96, v11
	v_fmac_f32_e32 v42, v92, v11
	v_fmac_f32_e32 v44, v96, v19
	v_and_b32_e32 v11, 0xffff0000, v2
	v_lshlrev_b32_e32 v2, 16, v2
	v_and_b32_e32 v19, 0xffff0000, v1
	v_lshlrev_b32_e32 v1, 16, v1
	v_fmac_f32_e32 v27, v88, v28
	v_fmac_f32_e32 v10, v96, v9
	v_fmac_f32_e32 v34, v96, v24
	v_fmac_f32_e32 v36, v92, v24
	v_fmac_f32_e32 v38, v92, v22
	v_fmac_f32_e32 v42, v96, v12
	v_and_b32_e32 v9, 0xffff0000, v3
	v_lshlrev_b32_e32 v3, 16, v3
	v_and_b32_e32 v21, 0xffff0000, v0
	v_lshlrev_b32_e32 v0, 16, v0
	v_fma_f32 v12, v84, v17, v90
	v_fma_f32 v24, v84, v1, v90
	v_fma_f32 v28, v84, v2, v90
	v_fmac_f32_e32 v8, v96, v26
	v_fmac_f32_e32 v38, v96, v14
	v_fmac_f32_e32 v12, v86, v0
	v_fma_f32 v14, v84, v0, v90
	v_fmac_f32_e32 v24, v86, v19
	v_fma_f32 v26, v84, v19, v90
	v_fmac_f32_e32 v28, v86, v11
	v_fma_f32 v30, v84, v11, v90
	v_fma_f32 v32, v84, v3, v90
	s_waitcnt vmcnt(0)
	v_and_b32_e32 v0, 0xffff0000, v4
	v_fmac_f32_e32 v24, v88, v2
	v_fmac_f32_e32 v26, v86, v2
	v_fmac_f32_e32 v28, v88, v3
	v_fmac_f32_e32 v30, v86, v3
	v_fmac_f32_e32 v32, v86, v9
	v_lshlrev_b32_e32 v3, 16, v4
	v_mov_b32_e32 v2, v0
	v_fmac_f32_e32 v30, v88, v9
	v_fmac_f32_e32 v32, v88, v16
	v_fma_f32 v9, v94, v20, v98
	v_pk_mul_f32 v[16:17], v[100:101], v[2:3]
	v_fmac_f32_e32 v36, v96, v22
	v_add_f32_e32 v2, v17, v9
	v_fmac_f32_e32 v14, v86, v21
	v_fma_f32 v22, v84, v21, v90
	v_add_f32_e32 v9, v16, v2
	v_and_b32_e32 v2, 0xffff0000, v5
	v_fmac_f32_e32 v14, v88, v1
	v_fmac_f32_e32 v22, v86, v1
	v_fmac_f32_e32 v26, v88, v11
	v_and_b32_e32 v1, 16, v4
	v_fma_f32 v11, v94, v3, v98
	v_and_b32_e32 v3, 16, v5
	v_lshlrev_b32_e32 v5, 16, v5
	v_mov_b32_e32 v4, v2
	v_fma_f32 v16, v94, v0, v98
	v_pk_mov_b32 v[0:1], v[4:5], v[0:1] op_sel:[1,0]
	v_fma_f32 v17, v94, v2, v98
	v_pk_mul_f32 v[0:1], v[100:101], v[0:1]
	v_fmac_f32_e32 v12, v88, v21
	v_add_f32_e32 v1, v1, v11
	v_add_f32_e32 v11, v0, v1
	v_pk_mul_f32 v[0:1], v[100:101], v[4:5]
	v_fmac_f32_e32 v22, v88, v19
	v_add_f32_e32 v1, v1, v16
	v_add_f32_e32 v35, v0, v1
	v_and_b32_e32 v0, 0xffff0000, v6
	v_fma_f32 v16, v94, v5, v98
	v_lshlrev_b32_e32 v5, 16, v6
	v_mov_b32_e32 v4, v0
	v_pk_mov_b32 v[2:3], v[4:5], v[2:3] op_sel:[1,0]
	v_and_b32_e32 v1, 16, v6
	v_pk_mul_f32 v[2:3], v[100:101], v[2:3]
	v_lshl_add_u64 v[120:121], v[70:71], 1, s[90:91]
	v_add_f32_e32 v3, v3, v16
	v_add_f32_e32 v37, v2, v3
	v_pk_mul_f32 v[2:3], v[100:101], v[4:5]
	v_fma_f32 v4, v94, v5, v98
	v_add_f32_e32 v3, v3, v17
	v_add_f32_e32 v39, v2, v3
	v_and_b32_e32 v2, 0xffff0000, v7
	v_lshlrev_b32_e32 v3, 16, v7
	v_fma_f32 v5, v94, v0, v98
	v_pk_mov_b32 v[0:1], v[2:3], v[0:1] op_sel:[1,0]
	v_mov_b32_e32 v16, 0
	v_pk_mul_f32 v[0:1], v[100:101], v[0:1]
	v_lshl_add_u64 v[128:129], v[72:73], 1, s[90:91]
	v_add_f32_e32 v1, v1, v4
	v_add_f32_e32 v41, v0, v1
	v_pk_mul_f32 v[0:1], v[100:101], v[2:3]
	v_fma_f32 v4, v94, v3, v98
	v_add_f32_e32 v1, v1, v5
	v_mov_b32_e32 v3, v18
	v_add_f32_e32 v43, v0, v1
	v_pk_mul_f32 v[0:1], v[102:103], v[2:3]
	v_pk_mul_f32 v[2:3], v[14:15], v[10:11]
	v_add_f32_e32 v0, v0, v4
	v_add_f32_e32 v45, v0, v1
	v_pk_mul_f32 v[0:1], v[12:13], v[8:9]
	ds_write2_b64 v214, v[0:1], v[2:3] offset1:1
	v_pk_mul_f32 v[0:1], v[22:23], v[34:35]
	v_pk_mul_f32 v[2:3], v[24:25], v[36:37]
	ds_write2_b64 v214, v[0:1], v[2:3] offset0:2 offset1:3
	v_pk_mul_f32 v[0:1], v[26:27], v[38:39]
	v_pk_mul_f32 v[2:3], v[28:29], v[40:41]
	ds_write2_b64 v214, v[0:1], v[2:3] offset0:4 offset1:5
	v_pk_mul_f32 v[0:1], v[30:31], v[42:43]
	v_pk_mul_f32 v[2:3], v[32:33], v[44:45]
	ds_write2_b64 v214, v[0:1], v[2:3] offset0:6 offset1:7
	global_load_dwordx4 v[0:3], v[120:121], off
	v_mov_b32_e32 v18, 0
	v_mov_b32_e32 v244, 0
	s_and_saveexec_b64 s[40:41], s[16:17]
	s_cbranch_execz .LBB0_327
	global_load_ushort v244, v[128:129], off offset:-2
	s_nop 0
	s_nop 0
.LBB0_327:
	s_or_b64 exec, exec, s[40:41]
	v_mov_b32_e32 v245, 0
	s_and_saveexec_b64 s[40:41], s[18:19]
	s_cbranch_execz .LBB0_329
	global_load_ushort v245, v[120:121], off offset:16
	s_nop 0
	s_nop 0
.LBB0_329:
	s_or_b64 exec, exec, s[40:41]
	v_lshl_add_u64 v[122:123], v[70:71], 1, s[92:93]
	global_load_dwordx4 v[8:11], v[122:123], off
	v_mov_b32_e32 v19, 0
	v_lshl_add_u64 v[130:131], v[72:73], 1, s[92:93]
	v_mov_b32_e32 v21, 0
	v_mov_b32_e32 v246, 0
	s_and_saveexec_b64 s[40:41], s[16:17]
	s_cbranch_execz .LBB0_331
	global_load_ushort v246, v[130:131], off offset:-2
	s_nop 0
	s_nop 0
.LBB0_331:
	s_or_b64 exec, exec, s[40:41]
	v_mov_b32_e32 v247, 0
	s_and_saveexec_b64 s[40:41], s[18:19]
	s_cbranch_execz .LBB0_333
	global_load_ushort v247, v[122:123], off offset:16
	s_nop 0
	s_nop 0
.LBB0_333:
	s_or_b64 exec, exec, s[40:41]
	v_lshl_add_u64 v[124:125], v[70:71], 1, s[94:95]
	global_load_dwordx4 v[12:15], v[124:125], off
	v_mov_b32_e32 v22, 0
	v_lshl_add_u64 v[132:133], v[72:73], 1, s[94:95]
	v_mov_b32_e32 v23, 0
	v_mov_b32_e32 v248, 0
	s_and_saveexec_b64 s[40:41], s[16:17]
	s_cbranch_execz .LBB0_335
	global_load_ushort v248, v[132:133], off offset:-2
	s_nop 0
	s_nop 0
.LBB0_335:
	s_or_b64 exec, exec, s[40:41]
	v_mov_b32_e32 v249, 0
	s_and_saveexec_b64 s[40:41], s[18:19]
	s_cbranch_execz .LBB0_337
	global_load_ushort v249, v[124:125], off offset:16
	s_nop 0
	s_nop 0
.LBB0_337:
	s_or_b64 exec, exec, s[40:41]
	v_lshl_add_u64 v[126:127], v[70:71], 1, s[96:97]
	global_load_dwordx4 v[4:7], v[126:127], off
	v_mov_b32_e32 v17, 0
	v_lshl_add_u64 v[134:135], v[72:73], 1, s[96:97]
	v_mov_b32_e32 v20, 0
	v_mov_b32_e32 v250, 0
	s_and_saveexec_b64 s[40:41], s[16:17]
	s_cbranch_execz .LBB0_339
	global_load_ushort v250, v[134:135], off offset:-2
	s_nop 0
	s_nop 0
.LBB0_339:
	s_or_b64 exec, exec, s[40:41]
	v_mov_b32_e32 v251, 0
	s_and_saveexec_b64 s[40:41], s[18:19]
	s_cbranch_execz .LBB0_341
	global_load_ushort v251, v[126:127], off offset:16
	s_nop 0
	s_nop 0
.LBB0_341:
	s_or_b64 exec, exec, s[40:41]
	s_waitcnt vmcnt(0)
	v_lshlrev_b32_e32 v18, 16, v244
	v_lshlrev_b32_e32 v16, 16, v245
	v_lshlrev_b32_e32 v21, 16, v246
	v_lshlrev_b32_e32 v19, 16, v247
	v_lshlrev_b32_e32 v23, 16, v248
	v_lshlrev_b32_e32 v22, 16, v249
	v_lshlrev_b32_e32 v20, 16, v250
	v_lshlrev_b32_e32 v17, 16, v251
	s_waitcnt vmcnt(1)
	v_and_b32_e32 v29, 0xffff0000, v12
	v_lshlrev_b32_e32 v12, 16, v12
	v_and_b32_e32 v24, 0xffff0000, v15
	v_lshlrev_b32_e32 v26, 16, v15
	v_and_b32_e32 v27, 0xffff0000, v13
	v_lshlrev_b32_e32 v25, 16, v13
	v_fma_f32 v13, v84, v23, v90
	v_fma_f32 v15, v84, v12, v90
	v_and_b32_e32 v28, 0xffff0000, v14
	v_lshlrev_b32_e32 v14, 16, v14
	v_fmac_f32_e32 v13, v86, v12
	v_fmac_f32_e32 v15, v86, v29
	v_fma_f32 v23, v84, v29, v90
	v_fma_f32 v33, v84, v26, v90
	v_fmac_f32_e32 v13, v88, v29
	v_fmac_f32_e32 v15, v88, v25
	v_fmac_f32_e32 v23, v86, v25
	v_fma_f32 v25, v84, v25, v90
	v_fma_f32 v29, v84, v14, v90
	v_fmac_f32_e32 v33, v86, v24
	v_fmac_f32_e32 v23, v88, v27
	v_fmac_f32_e32 v25, v86, v27
	v_fma_f32 v27, v84, v27, v90
	v_fmac_f32_e32 v29, v86, v28
	v_fma_f32 v31, v84, v28, v90
	v_fmac_f32_e32 v33, v88, v22
	v_and_b32_e32 v12, 0xffff0000, v11
	v_lshlrev_b32_e32 v11, 16, v11
	v_lshlrev_b32_e32 v22, 16, v10
	v_fmac_f32_e32 v25, v88, v14
	v_fmac_f32_e32 v27, v86, v14
	v_fmac_f32_e32 v29, v88, v26
	v_fmac_f32_e32 v31, v86, v26
	v_and_b32_e32 v14, 0xffff0000, v10
	v_and_b32_e32 v26, 0xffff0000, v8
	v_fma_f32 v40, v94, v22, v98
	v_fma_f32 v44, v94, v11, v98
	v_fmac_f32_e32 v31, v88, v24
	v_and_b32_e32 v24, 0xffff0000, v9
	v_lshlrev_b32_e32 v9, 16, v9
	v_lshlrev_b32_e32 v10, 16, v8
	v_fma_f32 v8, v94, v21, v98
	v_fma_f32 v34, v94, v26, v98
	v_fmac_f32_e32 v40, v92, v14
	v_fma_f32 v42, v94, v14, v98
	v_fmac_f32_e32 v44, v92, v12
	v_fmac_f32_e32 v8, v92, v10
	v_fma_f32 v10, v94, v10, v98
	v_fmac_f32_e32 v34, v92, v9
	v_fma_f32 v36, v94, v9, v98
	v_fma_f32 v38, v94, v24, v98
	v_fmac_f32_e32 v40, v96, v11
	v_fmac_f32_e32 v42, v92, v11
	v_fmac_f32_e32 v44, v96, v19
	v_and_b32_e32 v11, 0xffff0000, v2
	v_lshlrev_b32_e32 v2, 16, v2
	v_and_b32_e32 v19, 0xffff0000, v1
	v_lshlrev_b32_e32 v1, 16, v1
	v_fmac_f32_e32 v27, v88, v28
	v_fmac_f32_e32 v10, v92, v26
	v_fmac_f32_e32 v34, v96, v24
	v_fmac_f32_e32 v36, v92, v24
	v_fmac_f32_e32 v38, v92, v22
	v_fmac_f32_e32 v42, v96, v12
	v_and_b32_e32 v21, 0xffff0000, v0
	v_lshlrev_b32_e32 v0, 16, v0
	v_fma_f32 v12, v84, v18, v90
	v_fma_f32 v24, v84, v1, v90
	v_fma_f32 v28, v84, v2, v90
	v_fmac_f32_e32 v8, v96, v26
	v_fmac_f32_e32 v10, v96, v9
	v_fmac_f32_e32 v36, v96, v22
	v_fmac_f32_e32 v38, v96, v14
	v_and_b32_e32 v9, 0xffff0000, v3
	v_lshlrev_b32_e32 v3, 16, v3
	v_fmac_f32_e32 v12, v86, v0
	v_fma_f32 v14, v84, v0, v90
	v_fma_f32 v22, v84, v21, v90
	v_fmac_f32_e32 v24, v86, v19
	v_fma_f32 v26, v84, v19, v90
	v_fmac_f32_e32 v28, v86, v11
	v_fma_f32 v30, v84, v11, v90
	s_waitcnt vmcnt(0)
	v_and_b32_e32 v0, 0xffff0000, v4
	v_fmac_f32_e32 v22, v86, v1
	v_fmac_f32_e32 v24, v88, v2
	v_fmac_f32_e32 v26, v86, v2
	v_fmac_f32_e32 v28, v88, v3
	v_fmac_f32_e32 v30, v86, v3
	v_fma_f32 v32, v84, v3, v90
	v_lshlrev_b32_e32 v3, 16, v4
	v_mov_b32_e32 v2, v0
	v_fmac_f32_e32 v22, v88, v19
	v_fmac_f32_e32 v30, v88, v9
	v_fmac_f32_e32 v32, v86, v9
	v_fma_f32 v9, v94, v20, v98
	v_pk_mul_f32 v[18:19], v[100:101], v[2:3]
	v_fmac_f32_e32 v14, v86, v21
	v_add_f32_e32 v2, v19, v9
	v_add_f32_e32 v9, v18, v2
	v_and_b32_e32 v2, 0xffff0000, v5
	v_fmac_f32_e32 v14, v88, v1
	v_fmac_f32_e32 v26, v88, v11
	v_and_b32_e32 v1, 16, v4
	v_fma_f32 v11, v94, v3, v98
	v_and_b32_e32 v3, 16, v5
	v_lshlrev_b32_e32 v5, 16, v5
	v_mov_b32_e32 v4, v2
	v_fmac_f32_e32 v32, v88, v16
	v_fma_f32 v16, v94, v0, v98
	v_pk_mov_b32 v[0:1], v[4:5], v[0:1] op_sel:[1,0]
	v_fma_f32 v18, v94, v2, v98
	v_pk_mul_f32 v[0:1], v[100:101], v[0:1]
	v_fmac_f32_e32 v12, v88, v21
	v_add_f32_e32 v1, v1, v11
	v_add_f32_e32 v11, v0, v1
	v_pk_mul_f32 v[0:1], v[100:101], v[4:5]
	s_nop 0
	v_add_f32_e32 v1, v1, v16
	v_add_f32_e32 v35, v0, v1
	v_and_b32_e32 v0, 0xffff0000, v6
	v_fma_f32 v16, v94, v5, v98
	v_lshlrev_b32_e32 v5, 16, v6
	v_mov_b32_e32 v4, v0
	v_pk_mov_b32 v[2:3], v[4:5], v[2:3] op_sel:[1,0]
	v_and_b32_e32 v1, 16, v6
	v_pk_mul_f32 v[2:3], v[100:101], v[2:3]
	s_nop 0
	v_add_f32_e32 v3, v3, v16
	v_add_f32_e32 v37, v2, v3
	v_pk_mul_f32 v[2:3], v[100:101], v[4:5]
	v_fma_f32 v4, v94, v5, v98
	v_add_f32_e32 v3, v3, v18
	v_add_f32_e32 v39, v2, v3
	v_and_b32_e32 v2, 0xffff0000, v7
	v_lshlrev_b32_e32 v3, 16, v7
	v_fma_f32 v5, v94, v0, v98
	v_pk_mov_b32 v[0:1], v[2:3], v[0:1] op_sel:[1,0]
	s_nop 0
	v_pk_mul_f32 v[0:1], v[100:101], v[0:1]
	s_nop 0
	v_add_f32_e32 v1, v1, v4
	v_add_f32_e32 v41, v0, v1
	v_pk_mul_f32 v[0:1], v[100:101], v[2:3]
	v_fma_f32 v4, v94, v3, v98
	v_add_f32_e32 v1, v1, v5
	v_mov_b32_e32 v3, v17
	v_add_f32_e32 v43, v0, v1
	v_pk_mul_f32 v[0:1], v[102:103], v[2:3]
	v_pk_mul_f32 v[2:3], v[14:15], v[10:11]
	v_add_f32_e32 v0, v0, v4
	v_add_f32_e32 v45, v0, v1
	v_pk_mul_f32 v[0:1], v[12:13], v[8:9]
	ds_write2_b64 v215, v[0:1], v[2:3] offset1:1
	v_pk_mul_f32 v[0:1], v[22:23], v[34:35]
	v_pk_mul_f32 v[2:3], v[24:25], v[36:37]
	ds_write2_b64 v215, v[0:1], v[2:3] offset0:2 offset1:3
	v_pk_mul_f32 v[0:1], v[26:27], v[38:39]
	v_pk_mul_f32 v[2:3], v[28:29], v[40:41]
	ds_write2_b64 v215, v[0:1], v[2:3] offset0:4 offset1:5
	v_pk_mul_f32 v[0:1], v[30:31], v[42:43]
	v_pk_mul_f32 v[2:3], v[32:33], v[44:45]
	ds_write2_b64 v215, v[0:1], v[2:3] offset0:6 offset1:7
	s_waitcnt lgkmcnt(0)
	s_barrier
	s_and_saveexec_b64 s[40:41], s[4:5]
	s_xor_b64 s[90:91], exec, s[40:41]
	s_cbranch_execz .LBB0_345
	s_mov_b64 s[92:93], 0
	v_mov_b32_e32 v0, v56

.LBB0_366:
	s_or_b64 exec, exec, s[90:91]
	s_waitcnt lgkmcnt(0)
	s_barrier
	global_load_dwordx4 v[4:7], v[104:105], off
	v_mov_b32_e32 v17, 0
	v_mov_b32_e32 v20, 0
	v_mov_b32_e32 v244, 0
	s_and_saveexec_b64 s[40:41], s[12:13]
	s_cbranch_execz .LBB0_368
	global_load_ushort v244, v[110:111], off offset:-2
	s_nop 0
	s_nop 0

.LBB0_370:
	s_or_b64 exec, exec, s[40:41]
	global_load_dwordx4 v[8:11], v[106:107], off
	v_mov_b32_e32 v25, 0
	v_mov_b32_e32 v26, 0
	v_mov_b32_e32 v246, 0
	s_and_saveexec_b64 s[40:41], s[12:13]
	s_cbranch_execz .LBB0_372
	global_load_ushort v246, v[114:115], off offset:-2
	s_nop 0
	s_nop 0

.LBB0_374:
	s_or_b64 exec, exec, s[40:41]
	global_load_dwordx4 v[12:15], v[108:109], off
	v_mov_b32_e32 v29, 0
	v_mov_b32_e32 v30, 0
	v_mov_b32_e32 v248, 0
	s_and_saveexec_b64 s[40:41], s[12:13]
	s_cbranch_execz .LBB0_376
	global_load_ushort v248, v[116:117], off offset:-2
	s_nop 0
	s_nop 0

.LBB0_378:
	s_or_b64 exec, exec, s[40:41]
	global_load_dwordx4 v[0:3], v[112:113], off
	v_mov_b32_e32 v23, 0
	v_mov_b32_e32 v18, 0
	v_mov_b32_e32 v250, 0
	s_and_saveexec_b64 s[40:41], s[12:13]
	s_cbranch_execz .LBB0_380
	global_load_ushort v250, v[118:119], off offset:-2
	s_nop 0
	s_nop 0

.LBB0_382:
	s_or_b64 exec, exec, s[40:41]
	s_waitcnt vmcnt(0)
	v_lshlrev_b32_e32 v20, 16, v244
	v_lshlrev_b32_e32 v17, 16, v245
	v_lshlrev_b32_e32 v26, 16, v246
	v_lshlrev_b32_e32 v25, 16, v247
	v_lshlrev_b32_e32 v30, 16, v248
	v_lshlrev_b32_e32 v29, 16, v249
	v_lshlrev_b32_e32 v18, 16, v250
	v_lshlrev_b32_e32 v23, 16, v251
	s_waitcnt vmcnt(1)
	v_lshlrev_b32_e32 v31, 16, v12
	v_and_b32_e32 v12, 0xffff0000, v12
	v_pk_fma_f32 v[38:39], v[84:85], v[30:31], v[90:91]
	v_mov_b32_e32 v30, v31
	v_mov_b32_e32 v31, v12
	v_and_b32_e32 v37, 16, v14
	v_and_b32_e32 v36, 0xffff0000, v13
	v_lshlrev_b32_e32 v13, 16, v13
	v_pk_fma_f32 v[30:31], v[86:87], v[30:31], v[38:39]
	v_lshlrev_b32_e32 v34, 16, v15
	v_pk_fma_f32 v[30:31], v[88:89], v[12:13], v[30:31]
	v_pk_fma_f32 v[38:39], v[84:85], v[12:13], v[90:91]
	v_pk_mov_b32 v[12:13], v[12:13], v[36:37] op_sel:[1,0]
	v_and_b32_e32 v32, 0xffff0000, v14
	v_and_b32_e32 v35, 0xffff0000, v15
	v_mov_b32_e32 v33, v34
	v_lshlrev_b32_e32 v15, 16, v14
	v_mov_b32_e32 v14, v36
	v_pk_fma_f32 v[12:13], v[86:87], v[12:13], v[38:39]
	v_lshlrev_b32_e32 v27, 16, v8
	v_pk_fma_f32 v[36:37], v[88:89], v[14:15], v[12:13]
	v_pk_fma_f32 v[12:13], v[84:85], v[14:15], v[90:91]
	v_pk_mov_b32 v[14:15], v[14:15], v[32:33] op_sel:[1,0]
	v_and_b32_e32 v8, 0xffff0000, v8
	v_pk_fma_f32 v[12:13], v[86:87], v[14:15], v[12:13]
	v_mov_b32_e32 v28, v35
	v_pk_fma_f32 v[38:39], v[88:89], v[32:33], v[12:13]
	v_pk_fma_f32 v[12:13], v[84:85], v[32:33], v[90:91]
	v_and_b32_e32 v33, 16, v10
	v_pk_fma_f32 v[12:13], v[86:87], v[34:35], v[12:13]
	v_pk_fma_f32 v[34:35], v[94:95], v[26:27], v[98:99]
	v_mov_b32_e32 v26, v27
	v_mov_b32_e32 v27, v8
	v_and_b32_e32 v32, 0xffff0000, v9
	v_lshlrev_b32_e32 v9, 16, v9
	v_pk_fma_f32 v[26:27], v[92:93], v[26:27], v[34:35]
	v_lshlrev_b32_e32 v14, 16, v11
	v_pk_fma_f32 v[26:27], v[96:97], v[8:9], v[26:27]
	v_pk_fma_f32 v[34:35], v[94:95], v[8:9], v[98:99]
	v_pk_mov_b32 v[8:9], v[8:9], v[32:33] op_sel:[1,0]
	v_pk_fma_f32 v[28:29], v[88:89], v[28:29], v[12:13]
	v_and_b32_e32 v12, 0xffff0000, v10
	v_and_b32_e32 v15, 0xffff0000, v11
	v_mov_b32_e32 v13, v14
	v_lshlrev_b32_e32 v11, 16, v10
	v_mov_b32_e32 v10, v32
	v_pk_fma_f32 v[8:9], v[92:93], v[8:9], v[34:35]
	v_lshlrev_b32_e32 v21, 16, v4
	v_pk_fma_f32 v[32:33], v[96:97], v[10:11], v[8:9]
	v_pk_fma_f32 v[8:9], v[94:95], v[10:11], v[98:99]
	v_pk_mov_b32 v[10:11], v[10:11], v[12:13] op_sel:[1,0]
	v_and_b32_e32 v4, 0xffff0000, v4
	v_pk_fma_f32 v[8:9], v[92:93], v[10:11], v[8:9]
	v_mov_b32_e32 v24, v15
	v_pk_fma_f32 v[34:35], v[96:97], v[12:13], v[8:9]
	v_pk_fma_f32 v[8:9], v[94:95], v[12:13], v[98:99]
	v_and_b32_e32 v13, 16, v6
	v_pk_fma_f32 v[8:9], v[92:93], v[14:15], v[8:9]
	v_pk_fma_f32 v[14:15], v[84:85], v[20:21], v[90:91]
	v_mov_b32_e32 v20, v21
	v_mov_b32_e32 v21, v4
	v_and_b32_e32 v12, 0xffff0000, v5
	v_lshlrev_b32_e32 v5, 16, v5
	v_pk_fma_f32 v[14:15], v[86:87], v[20:21], v[14:15]
	v_lshlrev_b32_e32 v10, 16, v7
	v_pk_fma_f32 v[14:15], v[88:89], v[4:5], v[14:15]
	v_pk_fma_f32 v[20:21], v[84:85], v[4:5], v[90:91]
	v_pk_mov_b32 v[4:5], v[4:5], v[12:13] op_sel:[1,0]
	v_pk_fma_f32 v[40:41], v[96:97], v[24:25], v[8:9]
	v_and_b32_e32 v8, 0xffff0000, v6
	v_and_b32_e32 v11, 0xffff0000, v7
	v_mov_b32_e32 v9, v10
	v_lshlrev_b32_e32 v7, 16, v6
	v_mov_b32_e32 v6, v12
	v_pk_fma_f32 v[4:5], v[86:87], v[4:5], v[20:21]
	v_mov_b32_e32 v16, v11
	v_pk_fma_f32 v[12:13], v[88:89], v[6:7], v[4:5]
	v_pk_fma_f32 v[4:5], v[84:85], v[6:7], v[90:91]
	v_pk_mov_b32 v[6:7], v[6:7], v[8:9] op_sel:[1,0]
	v_pk_mul_f32 v[14:15], v[14:15], v[26:27]
	v_pk_fma_f32 v[4:5], v[86:87], v[6:7], v[4:5]
	s_waitcnt vmcnt(0)
	v_and_b32_e32 v42, 0xffff0000, v2
	v_pk_fma_f32 v[20:21], v[88:89], v[8:9], v[4:5]
	v_pk_fma_f32 v[4:5], v[84:85], v[8:9], v[90:91]
	v_pk_mul_f32 v[20:21], v[20:21], v[34:35]
	v_pk_fma_f32 v[4:5], v[86:87], v[10:11], v[4:5]
	ds_read2_b64 v[8:11], v214 offset0:2 offset1:3
	v_pk_fma_f32 v[16:17], v[88:89], v[16:17], v[4:5]
	ds_read2_b64 v[4:7], v214 offset1:1
	v_pk_mul_f32 v[16:17], v[16:17], v[40:41]
	v_lshlrev_b32_e32 v19, 16, v0
	s_waitcnt lgkmcnt(1)
	v_mov_b32_e32 v26, v8
	v_mov_b32_e32 v27, v10
	s_waitcnt lgkmcnt(0)
	v_mov_b32_e32 v24, v4
	v_mov_b32_e32 v25, v6
	v_pk_fma_f32 v[44:45], v[82:83], v[14:15], v[24:25]
	v_pk_mul_f32 v[24:25], v[12:13], v[32:33]
	ds_read2_b64 v[12:15], v214 offset0:4 offset1:5
	v_pk_fma_f32 v[32:33], v[82:83], v[24:25], v[26:27]
	ds_read2_b64 v[24:27], v214 offset0:6 offset1:7
	v_and_b32_e32 v0, 0xffff0000, v0
	v_pk_fma_f32 v[48:49], v[94:95], v[18:19], v[98:99]
	s_waitcnt lgkmcnt(1)
	v_mov_b32_e32 v34, v12
	v_mov_b32_e32 v35, v14
	v_pk_fma_f32 v[20:21], v[82:83], v[20:21], v[34:35]
	s_waitcnt lgkmcnt(0)
	v_mov_b32_e32 v34, v24
	v_mov_b32_e32 v35, v26
	v_pk_fma_f32 v[16:17], v[82:83], v[16:17], v[34:35]
	v_lshlrev_b32_e32 v34, 16, v3
	v_mov_b32_e32 v43, v34
	v_and_b32_e32 v35, 0xffff0000, v3
	v_pk_fma_f32 v[40:41], v[94:95], v[42:43], v[98:99]
	v_mov_b32_e32 v18, v19
	v_mov_b32_e32 v19, v0
	v_pk_fma_f32 v[40:41], v[92:93], v[34:35], v[40:41]
	v_mov_b32_e32 v22, v35
	v_and_b32_e32 v35, 16, v2
	v_and_b32_e32 v34, 0xffff0000, v1
	v_lshlrev_b32_e32 v1, 16, v1
	v_pk_fma_f32 v[18:19], v[92:93], v[18:19], v[48:49]
	v_pk_fma_f32 v[46:47], v[94:95], v[0:1], v[98:99]
	v_pk_fma_f32 v[18:19], v[96:97], v[0:1], v[18:19]
	v_pk_mov_b32 v[0:1], v[0:1], v[34:35] op_sel:[1,0]
	v_lshlrev_b32_e32 v3, 16, v2
	v_mov_b32_e32 v2, v34
	v_pk_fma_f32 v[0:1], v[92:93], v[0:1], v[46:47]
	s_lshl_b32 s33, s80, 11
	v_pk_fma_f32 v[0:1], v[96:97], v[2:3], v[0:1]
	s_add_i32 s40, s33, s82
	v_pk_mul_f32 v[18:19], v[30:31], v[18:19]
	v_mov_b32_e32 v6, v5
	v_pk_mul_f32 v[0:1], v[36:37], v[0:1]
	v_mov_b32_e32 v10, v9
	s_ashr_i32 s41, s40, 31
	v_pk_fma_f32 v[22:23], v[96:97], v[22:23], v[40:41]
	v_pk_fma_f32 v[40:41], v[94:95], v[2:3], v[98:99]
	v_pk_fma_f32 v[4:5], v[82:83], v[18:19], v[6:7]
	v_pk_fma_f32 v[6:7], v[82:83], v[0:1], v[10:11]
	v_pk_mov_b32 v[0:1], v[2:3], v[42:43] op_sel:[1,0]
	s_lshl_b64 s[40:41], s[40:41], 14
	v_pk_fma_f32 v[0:1], v[92:93], v[0:1], v[40:41]
	s_add_u32 s92, s8, s40
	v_pk_fma_f32 v[0:1], v[96:97], v[42:43], v[0:1]
	s_addc_u32 s93, s9, s41
	v_pk_mul_f32 v[0:1], v[38:39], v[0:1]
	v_mov_b32_e32 v14, v13
	s_add_u32 s90, s92, 0x1000000
	v_pk_fma_f32 v[8:9], v[82:83], v[0:1], v[14:15]
	v_pk_mul_f32 v[0:1], v[28:29], v[22:23]
	v_mov_b32_e32 v26, v25
	v_lshlrev_b64 v[12:13], 1, v[62:63]
	s_addc_u32 s91, s93, 0
	v_pk_fma_f32 v[10:11], v[82:83], v[0:1], v[26:27]
	v_cvt_pk_bf16_f32 v0, v44, v45
	v_cvt_pk_bf16_f32 v1, v32, v33
	v_cvt_pk_bf16_f32 v2, v20, v21
	v_cvt_pk_bf16_f32 v3, v16, v17
	v_lshl_add_u64 v[14:15], s[92:93], 0, v[12:13]
	global_store_dwordx4 v[14:15], v[0:3], off
	v_mov_b32_e32 v17, 0
	v_mov_b32_e32 v18, 0
	v_cvt_pk_bf16_f32 v0, v4, v5
	v_cvt_pk_bf16_f32 v1, v6, v7
	v_cvt_pk_bf16_f32 v2, v8, v9
	v_cvt_pk_bf16_f32 v3, v10, v11
	v_lshl_add_u64 v[4:5], s[90:91], 0, v[12:13]
	global_store_dwordx4 v[4:5], v[0:3], off
	global_load_dwordx4 v[0:3], v[120:121], off
	v_mov_b32_e32 v244, 0
	s_and_saveexec_b64 s[40:41], s[16:17]
	s_cbranch_execz .LBB0_384
	global_load_ushort v244, v[128:129], off offset:-2
	s_nop 0
	s_nop 0

.LBB0_386:
	s_or_b64 exec, exec, s[40:41]
	global_load_dwordx4 v[8:11], v[122:123], off
	v_mov_b32_e32 v25, 0
	v_mov_b32_e32 v26, 0
	v_mov_b32_e32 v246, 0
	s_and_saveexec_b64 s[40:41], s[16:17]
	s_cbranch_execz .LBB0_388
	global_load_ushort v246, v[130:131], off offset:-2
	s_nop 0
	s_nop 0

.LBB0_390:
	s_or_b64 exec, exec, s[40:41]
	global_load_dwordx4 v[12:15], v[124:125], off
	v_mov_b32_e32 v29, 0
	v_mov_b32_e32 v30, 0
	v_mov_b32_e32 v248, 0
	s_and_saveexec_b64 s[40:41], s[16:17]
	s_cbranch_execz .LBB0_392
	global_load_ushort v248, v[132:133], off offset:-2
	s_nop 0
	s_nop 0

.LBB0_394:
	s_or_b64 exec, exec, s[40:41]
	global_load_dwordx4 v[4:7], v[126:127], off
	v_mov_b32_e32 v23, 0
	v_mov_b32_e32 v20, 0
	v_mov_b32_e32 v250, 0
	s_and_saveexec_b64 s[40:41], s[16:17]
	s_cbranch_execz .LBB0_396
	global_load_ushort v250, v[134:135], off offset:-2
	s_nop 0
	s_nop 0
.LBB0_396:
	s_or_b64 exec, exec, s[40:41]
	v_mov_b32_e32 v251, 0
	s_and_saveexec_b64 s[40:41], s[18:19]
	s_cbranch_execz .LBB0_308
	global_load_ushort v251, v[126:127], off offset:16
	s_nop 0
	s_nop 0
	s_branch .LBB0_308

.LBB0_492:
	v_lshlrev_b32_e32 v54, 16, v3
	v_lshlrev_b32_e32 v25, 16, v0
	v_and_b32_e32 v52, 0xffff0000, v2
	v_mov_b32_e32 v53, v54
	v_and_b32_e32 v0, 0xffff0000, v0
	v_and_b32_e32 v55, 0xffff0000, v3
	v_pk_fma_f32 v[58:59], v[32:33], v[52:53], v[34:35] op_sel_hi:[0,1,0]
	v_lshlrev_b32_e32 v60, 16, v5
	v_and_b32_e32 v61, 0xffff0000, v5
	v_lshlrev_b32_e32 v64, 16, v4
	v_and_b32_e32 v65, 0xffff0000, v4
	v_pk_fma_f32 v[4:5], v[32:33], v[24:25], v[34:35] op_sel_hi:[0,1,0]
	v_mov_b32_e32 v24, v25
	v_mov_b32_e32 v25, v0
	v_pk_fma_f32 v[58:59], v[28:29], v[54:55], v[58:59] op_sel_hi:[0,1,1]
	v_mov_b32_e32 v26, v55
	v_and_b32_e32 v55, 16, v2
	v_and_b32_e32 v54, 0xffff0000, v1
	v_lshlrev_b32_e32 v1, 16, v1
	v_pk_fma_f32 v[4:5], v[28:29], v[24:25], v[4:5] op_sel_hi:[0,1,1]
	v_pk_fma_f32 v[62:63], v[32:33], v[0:1], v[34:35] op_sel_hi:[0,1,0]
	v_pk_fma_f32 v[4:5], v[30:31], v[0:1], v[4:5] op_sel_hi:[0,1,1]
	v_pk_mov_b32 v[0:1], v[0:1], v[54:55] op_sel:[1,0]
	v_lshlrev_b32_e32 v3, 16, v2
	v_mov_b32_e32 v2, v54
	v_pk_fma_f32 v[0:1], v[28:29], v[0:1], v[62:63] op_sel_hi:[0,1,1]
	v_pk_fma_f32 v[0:1], v[30:31], v[2:3], v[0:1] op_sel_hi:[0,1,1]
	v_lshlrev_b32_e32 v56, 16, v7
	v_and_b32_e32 v57, 0xffff0000, v7
	v_pk_fma_f32 v[26:27], v[30:31], v[26:27], v[58:59] op_sel_hi:[0,1,1]
	v_lshlrev_b32_e32 v58, 16, v6
	v_and_b32_e32 v59, 0xffff0000, v6
	v_pk_fma_f32 v[6:7], v[32:33], v[2:3], v[34:35] op_sel_hi:[0,1,0]
	v_pk_mul_f32 v[24:25], v[0:1], v[60:61]
	v_pk_mov_b32 v[0:1], v[2:3], v[52:53] op_sel:[1,0]
	s_lshr_b32 s0, s19, 4
	v_pk_fma_f32 v[0:1], v[28:29], v[0:1], v[6:7] op_sel_hi:[0,1,1]
	v_pk_fma_f32 v[0:1], v[30:31], v[52:53], v[0:1] op_sel_hi:[0,1,1]
	v_pk_mul_f32 v[4:5], v[4:5], v[64:65]
	v_pk_mul_f32 v[2:3], v[0:1], v[58:59]
	v_pk_mul_f32 v[6:7], v[26:27], v[56:57]
	s_cmpk_lt_i32 s19, 0x4000
	v_cvt_pk_bf16_f32 v0, v4, v5
	v_cvt_pk_bf16_f32 v1, v24, v25
	v_cvt_pk_bf16_f32 v2, v2, v3
	v_cvt_pk_bf16_f32 v3, v6, v7
	s_cselect_b32 s2, 0x7f, 3
	s_barrier
	ds_write_b128 v46, v[0:3]
	s_waitcnt lgkmcnt(0)
	s_barrier
	ds_read_u16 v0, v47
	ds_read_u16 v1, v47 offset:144
	ds_read_u16 v2, v47 offset:288
	ds_read_u16 v3, v47 offset:432
	ds_read_u16 v4, v47 offset:576
	ds_read_u16 v5, v47 offset:720
	ds_read_u16 v6, v47 offset:864
	ds_read_u16 v7, v47 offset:1008
	s_cselect_b32 s3, s18, 0x7fffff00
	s_and_b32 s0, s2, s0
	s_and_b32 s2, s3, s13
	s_lshl_b32 s0, s0, 6
	s_waitcnt lgkmcnt(7)
	v_lshlrev_b32_e32 v0, 16, v0
	s_waitcnt lgkmcnt(6)
	v_lshlrev_b32_e32 v1, 16, v1
	s_waitcnt lgkmcnt(5)
	v_lshlrev_b32_e32 v2, 16, v2
	s_waitcnt lgkmcnt(4)
	v_lshlrev_b32_e32 v3, 16, v3
	s_waitcnt lgkmcnt(3)
	v_lshlrev_b32_e32 v4, 16, v4
	s_waitcnt lgkmcnt(2)
	v_lshlrev_b32_e32 v5, 16, v5
	s_add_i32 s0, s0, s2
	v_cvt_pk_bf16_f32 v0, v0, v1
	v_cvt_pk_bf16_f32 v1, v2, v3
	v_cvt_pk_bf16_f32 v2, v4, v5
	v_add_u32_e32 v4, s0, v29
	v_ashrrev_i32_e32 v5, 31, v4
	v_readlane_b32 s2, v243, 54
	v_lshlrev_b64 v[4:5], 11, v[4:5]
	v_readlane_b32 s3, v243, 55
	s_and_b32 s0, s11, 0x3c0
	s_lshl_b32 s0, s0, 1
	v_lshl_add_u64 v[4:5], s[2:3], 0, v[4:5]
	s_waitcnt lgkmcnt(1)
	v_lshlrev_b32_e32 v6, 16, v6
	s_waitcnt lgkmcnt(0)
	v_lshlrev_b32_e32 v7, 16, v7
	v_lshl_add_u64 v[4:5], v[4:5], 0, s[0:1]
	v_mov_b32_e32 v41, v39
	v_cvt_pk_bf16_f32 v3, v6, v7
	v_lshl_add_u64 v[4:5], v[4:5], 0, v[40:41]
	global_store_dwordx4 v[4:5], v[0:3], off
	s_add_i32 s19, s19, s66
	s_add_i32 s11, s11, s12
	s_add_i32 s13, s13, s14
	v_mov_b64_e32 v[0:1], v[16:17]
	v_mov_b64_e32 v[4:5], v[12:13]
	s_cmpk_lt_i32 s19, 0x4200
	v_mov_b32_e32 v34, v45
	v_mov_b32_e32 v30, v44
	v_mov_b32_e32 v28, v33
	v_mov_b32_e32 v32, v31
	s_waitcnt vmcnt(4)
	v_mov_b32_e32 v31, v38
	v_lshlrev_b32_e32 v35, 16, v244
	v_lshlrev_b32_e32 v37, 16, v245
	s_waitcnt vmcnt(3)
	v_mov_b32_e32 v33, v42
	s_waitcnt vmcnt(2)
	v_mov_b32_e32 v44, v43
	s_waitcnt vmcnt(1)
	v_mov_b32_e32 v45, v50
	v_mov_b64_e32 v[2:3], v[18:19]
	v_mov_b64_e32 v[6:7], v[14:15]
	v_mov_b32_e32 v24, v49
	v_mov_b32_e32 v27, v48
	s_cbranch_scc0 .LBB0_502

.LBB0_498:
	s_add_i32 s5, s15, s11
	v_lshl_or_b32 v22, s20, 6, v36
	v_readlane_b32 s20, v243, 56
	s_and_b32 s5, s5, 0x3c0
	v_readlane_b32 s21, v243, 57
	v_add_u32_e32 v42, s5, v29
	s_ashr_i32 s5, s4, 31
	v_mov_b64_e32 v[8:9], s[20:21]
	v_mad_i64_i32 v[8:9], s[20:21], v42, s16, v[8:9]
	v_lshl_add_u64 v[8:9], s[4:5], 1, v[8:9]
	v_lshlrev_b32_e32 v38, 1, v22
	v_lshl_add_u64 v[20:21], v[8:9], 0, v[38:39]
	global_load_dwordx4 v[8:11], v[20:21], off
	v_cmp_ne_u32_e32 vcc, 0, v22
	v_mov_b32_e32 v245, 0
	v_mov_b32_e32 v244, 0
	s_and_saveexec_b64 s[4:5], vcc
	s_cbranch_execz .LBB0_500
	global_load_ushort v244, v[20:21], off offset:-2
	s_nop 0
	s_nop 0
.LBB0_500:
	s_or_b64 exec, exec, s[4:5]
	v_add_u32_e32 v22, 8, v22
	v_cmp_gt_u32_e32 vcc, s6, v22
	s_and_saveexec_b64 s[4:5], vcc
	s_cbranch_execz .LBB0_491
	global_load_ushort v245, v[20:21], off offset:16
	s_nop 0
	s_nop 0
	s_branch .LBB0_491
